# last in-loop cooperative-groups grid sync also replaced by the two-level barrier (24 of 25 syncs)
# speedup vs baseline: 1.0034x; 1.0034x over previous
; __global__ void __launch_bounds__(NT) fwd_megakernel(Params p) {
;     ...
;     phase_final(p, hf);
;     grid.sync();
.LBB0_378:
	v_readlane_b32 s0, v254, 0
	v_readlane_b32 s1, v254, 1
	buffer_wbl2 sc1
	s_waitcnt vmcnt(0)
	v_readlane_b32 s0, v254, 2
	v_readlane_b32 s1, v254, 3
	v_readlane_b32 s24, v255, 50
	v_readlane_b32 s25, v254, 4
	v_readlane_b32 s80, v254, 5
	s_nop 3
	s_load_dwordx2 s[8:9], s[0:1], 0x128
	s_add_i32 s24, s24, 1
	v_writelane_b32 v255, s24, 50
	s_and_b32 s25, s25, 7
	s_sub_i32 s81, s80, s25
	s_add_i32 s81, s81, 7
	s_lshr_b32 s81, s81, 3
	s_mul_i32 s81, s81, s24
	s_min_u32 s80, s80, 8
	s_mul_i32 s80, s80, s24
	s_lshl_b32 s25, s25, 5
	v_mov_b32_e32 v0, s25
	v_mov_b32_e32 v1, 1
	s_waitcnt lgkmcnt(0)
	s_add_u32 s8, s8, 0x43a4000
	s_addc_u32 s9, s9, 0
	global_atomic_add v2, v0, v1, s[8:9] offset:512 sc0
	s_waitcnt vmcnt(0)
	v_readfirstlane_b32 s0, v2
	s_nop 3
	s_add_i32 s0, s0, 1
	s_cmp_eq_u32 s0, s81
	s_cbranch_scc0 .Lgs12_follower
	global_atomic_add v2, v153, v1, s[8:9] offset:64 sc0
	s_waitcnt vmcnt(0)
	v_readfirstlane_b32 s0, v2
	s_nop 3
	s_add_i32 s0, s0, 1
	s_cmp_eq_u32 s0, s80
	s_cbranch_scc0 .Lgs12_lwait
	global_atomic_add v153, v1, s[8:9] offset:128
	s_branch .Lgs12_lrel

; __global__ void __launch_bounds__(NT) fwd_megakernel(Params p) {
;     ...
;     grid.sync();
;   }
.Lgs12_done:
	s_getpc_b64 s[98:99]
